# phase order: PLE projection GEMM runs after the FFN2 down-projection (positions 6 and 7 trade work), so CAT is cache-resident for the PLE-gate epilogue
# speedup vs baseline: 1.0401x; 1.0392x over previous
; __global__ void __launch_bounds__(NWAVES * 64, 2) fwd_megakernel(Args args) {
;     ...
;         switch (j) {
;             case 0: g = pg8::Gemm{XB, W1, M, 2 * FF, DM}; E.mode = pg8::EPI_SWIGLU; E.ob = HB; E.ldc = FF; E.ss_in = ss; break;
;             case 1: g = pg8::Gemm{HB, WD1, M, DM, FF}; E.mode = pg8::EPI_RESID; E.xb_in = XB; E.ob = XB; E.ss_out = ss + M; E.alpha = 0.5f; break;
;             case 2: g = pg8::Gemm{XB, WQK, M, NQK, DM}; E.mode = pg8::EPI_BF16; E.ob = QKB; E.ldc = 0; E.ss_in = ss + M; break;
;             case 3: g = pg8::Gemm{WV, XB, NVT, M, DM}; E.mode = pg8::EPI_COLSCALE; E.ob = VT; E.ldc = M; E.ss_in = ss + M; break;
;             case 4: g = pg8::Gemm{CAT, WO, M, DM, DM}; E.mode = pg8::EPI_RESID; E.xb_in = XB; E.ob = XB; E.ss_out = ss + 2 * M; E.alpha = 1.0f; break;
;             case 5: g = pg8::Gemm{XB, W2, M, 2 * FF, DM}; E.mode = pg8::EPI_SWIGLU; E.ob = HB; E.ldc = FF; E.ss_in = ss + 2 * M; break;
;             case 6: g = pg8::Gemm{PB, WPP, M, DM, PLE}; E.mode = pg8::EPI_BF16; E.ob = CAT; E.ldc = DM; break;
;             case 7: g = pg8::Gemm{HB, WD2, M, DM, FF}; E.mode = pg8::EPI_RESID; E.xb_in = XB; E.ob = XB; E.ss_out = ss + 3 * M; E.alpha = 0.5f; break;
;             default: g = pg8::Gemm{XB, WPG, M, DM, DM}; E.mode = pg8::EPI_PLE; E.xb_in = XB; E.ob = HB; E.ss_in = ss + 3 * M; E.ss_out = ss + 4 * M; E.proj = CAT; break;
;         }
.LBB0_216:
	s_mov_b64 s[4:5], -1
	s_mov_b64 s[34:35], 0
	s_cmp_lt_i32 s39, 4
	s_mov_b64 s[2:3], 0
	s_mov_b64 s[40:41], 0
	s_mov_b64 s[42:43], 0
	s_mov_b64 s[86:87], 0
	s_mov_b64 s[8:9], 0
	s_cbranch_scc1 .LBB0_591
	s_cmp_gt_i32 s39, 5
	s_cbranch_scc0 .LBB0_220
	s_mov_b64 s[4:5], 0
	s_mov_b64 s[40:41], -1
	s_bitcmp0_b32 s39, 0
	s_cbranch_scc0 .LBB0_220
	s_cmp_eq_u32 s39, 6
	s_cselect_b64 s[42:43], -1, 0
	s_cmp_lg_u32 s39, 6
	s_cselect_b64 s[86:87], -1, 0
	s_mov_b64 s[40:41], 0

; __global__ void __launch_bounds__(NWAVES * 64, 2) fwd_megakernel(Args args) {
;     ...
;         switch (j) {
;             case 0: g = pg8::Gemm{XB, W1, M, 2 * FF, DM}; E.mode = pg8::EPI_SWIGLU; E.ob = HB; E.ldc = FF; E.ss_in = ss; break;
;             case 1: g = pg8::Gemm{HB, WD1, M, DM, FF}; E.mode = pg8::EPI_RESID; E.xb_in = XB; E.ob = XB; E.ss_out = ss + M; E.alpha = 0.5f; break;
;             case 2: g = pg8::Gemm{XB, WQK, M, NQK, DM}; E.mode = pg8::EPI_BF16; E.ob = QKB; E.ldc = 0; E.ss_in = ss + M; break;
;             case 3: g = pg8::Gemm{WV, XB, NVT, M, DM}; E.mode = pg8::EPI_COLSCALE; E.ob = VT; E.ldc = M; E.ss_in = ss + M; break;
;             case 4: g = pg8::Gemm{CAT, WO, M, DM, DM}; E.mode = pg8::EPI_RESID; E.xb_in = XB; E.ob = XB; E.ss_out = ss + 2 * M; E.alpha = 1.0f; break;
;             case 5: g = pg8::Gemm{XB, W2, M, 2 * FF, DM}; E.mode = pg8::EPI_SWIGLU; E.ob = HB; E.ldc = FF; E.ss_in = ss + 2 * M; break;
;             case 6: g = pg8::Gemm{PB, WPP, M, DM, PLE}; E.mode = pg8::EPI_BF16; E.ob = CAT; E.ldc = DM; break;
;             case 7: g = pg8::Gemm{HB, WD2, M, DM, FF}; E.mode = pg8::EPI_RESID; E.xb_in = XB; E.ob = XB; E.ss_out = ss + 3 * M; E.alpha = 0.5f; break;
;             default: g = pg8::Gemm{XB, WPG, M, DM, DM}; E.mode = pg8::EPI_PLE; E.xb_in = XB; E.ob = HB; E.ss_in = ss + 3 * M; E.ss_out = ss + 4 * M; E.proj = CAT; break;
;         }
.LBB0_609:
	s_cmp_lt_i32 s39, 4
	s_cbranch_scc1 .LBB0_632
	s_cmp_gt_i32 s39, 5
	s_mov_b64 s[8:9], -1
	s_cbranch_scc0 .LBB0_614
	s_bitcmp0_b32 s39, 0
	s_mov_b64 s[40:41], -1
	s_cbranch_scc0 .LBB0_613
	s_cmp_lg_u32 s39, 6
	s_mov_b64 s[42:43], -1
	s_mov_b64 s[40:41], 0
	s_cselect_b64 s[86:87], -1, 0
